# residual epilogue: all 16 base-tile loads issued back to back (vmcnt(0) after 8 -> vmcnt(8) after 16), on top of v22
# speedup vs baseline: 1.0126x; 1.0036x over previous
.LBB0_500:
	v_readlane_b32 s30, v255, 48
	v_lshl_add_u32 v228, s53, 8, v248
	v_lshl_or_b32 v4, s33, 8, v250
	v_readlane_b32 s31, v255, 49
	v_lshl_add_u32 v4, v228, 11, v4
	s_mov_b64 s[28:29], -1
	s_and_b64 vcc, exec, s[30:31]
	s_mov_b32 s57, 0x2e000
	s_mov_b32 s58, 0x44000
	s_mov_b32 s59, 0x5a000
	s_mov_b32 s60, 0x70000
	s_cbranch_vccz .LBB0_566
	v_lshl_add_u64 v[134:135], v[4:5], 1, s[18:19]
	v_add_co_u32_e32 v136, vcc, 0x10000, v134
	global_load_dwordx4 v[194:197], v[134:135], off
	global_load_dwordx4 v[190:193], v[134:135], off offset:256
	v_addc_co_u32_e32 v137, vcc, 0, v135, vcc
	global_load_dwordx4 v[186:189], v[136:137], off
	global_load_dwordx4 v[182:185], v[136:137], off offset:256
	v_add_co_u32_e32 v136, vcc, 0x20000, v134
	s_mov_b32 s28, 0xb0000
	s_nop 0
	v_addc_co_u32_e32 v137, vcc, 0, v135, vcc
	global_load_dwordx4 v[178:181], v[136:137], off
	global_load_dwordx4 v[174:177], v[136:137], off offset:256
	v_add_co_u32_e32 v136, vcc, 0x30000, v134
	v_mov_b32_e32 v219, v218
	s_nop 0
	v_addc_co_u32_e32 v137, vcc, 0, v135, vcc
	global_load_dwordx4 v[170:173], v[136:137], off
	global_load_dwordx4 v[166:169], v[136:137], off offset:256
	v_add_co_u32_e32 v136, vcc, 0x80000, v134
	s_nop 1
	v_addc_co_u32_e32 v137, vcc, 0, v135, vcc
	global_load_dwordx4 v[162:165], v[136:137], off
	global_load_dwordx4 v[158:161], v[136:137], off offset:256
	v_add_co_u32_e32 v136, vcc, 0x90000, v134
	s_nop 0
	s_nop 0
	v_addc_co_u32_e32 v137, vcc, 0, v135, vcc
	global_load_dwordx4 v[154:157], v[136:137], off
	global_load_dwordx4 v[150:153], v[136:137], off offset:256
	v_add_co_u32_e32 v136, vcc, 0xa0000, v134
	s_nop 0
	s_nop 0
	v_addc_co_u32_e32 v137, vcc, 0, v135, vcc
	v_add_co_u32_e32 v134, vcc, s28, v134
	global_load_dwordx4 v[146:149], v[136:137], off
	global_load_dwordx4 v[142:145], v[136:137], off offset:256
	v_addc_co_u32_e32 v135, vcc, 0, v135, vcc
	global_load_dwordx4 v[138:141], v[134:135], off
	s_nop 0
	global_load_dwordx4 v[134:137], v[134:135], off offset:256
	s_waitcnt vmcnt(8)
	v_lshlrev_b32_e32 v198, 16, v194
	v_and_b32_e32 v199, 0xffff0000, v194
	v_lshlrev_b32_e32 v194, 16, v195
	v_and_b32_e32 v195, 0xffff0000, v195
	v_lshlrev_b32_e32 v202, 16, v196
	v_and_b32_e32 v203, 0xffff0000, v196
	v_lshlrev_b32_e32 v200, 16, v197
	v_and_b32_e32 v201, 0xffff0000, v197
	v_pk_fma_f32 v[196:197], v[218:219], v[132:133], v[194:195]
	v_pk_fma_f32 v[194:195], v[222:223], v[130:131], v[198:199]
	v_pk_fma_f32 v[200:201], v[218:219], v[128:129], v[200:201]
	v_pk_fma_f32 v[198:199], v[222:223], v[126:127], v[202:203]
	s_mov_b64 s[28:29], -1
	s_and_b64 vcc, exec, s[16:17]
	s_cbranch_vccz .LBB0_503
	v_cvt_pk_bf16_f32 v202, v194, v195
	v_cvt_pk_bf16_f32 v203, v196, v197
	v_cvt_pk_bf16_f32 v204, v198, v199
	v_cvt_pk_bf16_f32 v205, v200, v201
	v_lshl_add_u64 v[206:207], v[4:5], 1, s[20:21]
	global_store_dwordx4 v[206:207], v[202:205], off
	s_mov_b64 s[28:29], 0
